# v16 + prologue w_in conversion items: both 16-row load batches of an item in flight together (second batch on fresh registers)
# speedup vs baseline: 1.0187x; 1.0090x over previous
; #define LAS __attribute__((address_space(3)))
; template <class KS>
; __device__ __forceinline__ void p0_transpose_item(const float* W, int K, int N, bf16* WT, int kb, int nb, int prow, LAS float* scr, int lane, const KS& ks) {
;     const int k0 = 64 * kb, n0 = 32 * nb;
; #pragma unroll 8
;     for (int i = 0; i < 32; ++i) { const int kk = 2 * i + (lane >> 5); scr[kk * 33 + (lane & 31)] = W[(size_t)(k0 + kk) * N + n0 + (lane & 31)] * ks(k0 + kk); }
; __device__ __forceinline__ void convert_items(KArgs A, unsigned char* ws, LAS unsigned char* lds, int it0, int it1, int gw, int NGW, int wave, int lane) {
;     ...
;         if (r < CI_IN) { const int kb = r / 112, nb = r % 112, pn = nb >> 3, cbk = nb & 7; const float* g1 = A->in.g1;
;             p0_transpose_item(A->in.win, DM, NIN, WIN, kb, nb, 256 * pn + 128 * (cbk & 1) + 32 * (cbk >> 1), scr, lane, [g1](int k) { return g1[k]; }); continue; } r -= CI_IN;
.LBB0_81:
	s_lshl_b32 s23, s11, 1
	s_lshl_b32 s36, s10, 1
	v_add_u32_e32 v50, s23, v34
	v_add_u32_e32 v52, s36, v29
	v_add_u32_e32 v54, s23, v36
	v_add_u32_e32 v56, s36, v31
	v_add_u32_e32 v72, s23, v38
	v_add_u32_e32 v74, s36, v35
	v_add_u32_e32 v76, s23, v40
	v_add_u32_e32 v78, s36, v37
	v_add_u32_e32 v80, s23, v42
	v_add_u32_e32 v82, s36, v39
	v_add_u32_e32 v84, s23, v44
	v_add_u32_e32 v86, s36, v41
	v_add_u32_e32 v88, s23, v46
	v_add_u32_e32 v90, s36, v43
	v_add_u32_e32 v92, s23, v48
	v_add_u32_e32 v94, s36, v45
	v_mad_i64_i32 v[96:97], s[38:39], v50, s33, v[32:33]
	v_ashrrev_i32_e32 v53, 31, v52
	v_ashrrev_i32_e32 v51, 31, v50
	v_ashrrev_i32_e32 v57, 31, v56
	v_ashrrev_i32_e32 v55, 31, v54
	v_ashrrev_i32_e32 v75, 31, v74
	v_ashrrev_i32_e32 v73, 31, v72
	v_ashrrev_i32_e32 v79, 31, v78
	v_ashrrev_i32_e32 v77, 31, v76
	v_mad_i64_i32 v[98:99], s[38:39], v52, s33, v[32:33]
	v_mad_i64_i32 v[100:101], s[38:39], v54, s33, v[32:33]
	v_mad_i64_i32 v[102:103], s[38:39], v56, s33, v[32:33]
	v_mad_i64_i32 v[104:105], s[38:39], v72, s33, v[32:33]
	v_mad_i64_i32 v[106:107], s[38:39], v74, s33, v[32:33]
	v_mad_i64_i32 v[108:109], s[38:39], v76, s33, v[32:33]
	v_mad_i64_i32 v[110:111], s[38:39], v78, s33, v[32:33]
	v_mad_i64_i32 v[112:113], s[38:39], v80, s33, v[32:33]
	v_ashrrev_i32_e32 v83, 31, v82
	v_ashrrev_i32_e32 v81, 31, v80
	v_mad_i64_i32 v[116:117], s[38:39], v84, s33, v[32:33]
	v_ashrrev_i32_e32 v87, 31, v86
	v_ashrrev_i32_e32 v85, 31, v84
	v_mad_i64_i32 v[120:121], s[38:39], v88, s33, v[32:33]
	v_ashrrev_i32_e32 v91, 31, v90
	v_ashrrev_i32_e32 v89, 31, v88
	v_mad_i64_i32 v[124:125], s[38:39], v92, s33, v[32:33]
	v_ashrrev_i32_e32 v95, 31, v94
	v_ashrrev_i32_e32 v93, 31, v92
	global_load_dword v96, v[96:97], off
	s_nop 0
	global_load_dword v97, v[98:99], off
	v_lshl_add_u64 v[50:51], v[50:51], 2, s[8:9]
	v_lshl_add_u64 v[52:53], v[52:53], 2, s[8:9]
	v_lshl_add_u64 v[54:55], v[54:55], 2, s[8:9]
	v_lshl_add_u64 v[56:57], v[56:57], 2, s[8:9]
	v_lshl_add_u64 v[72:73], v[72:73], 2, s[8:9]
	v_lshl_add_u64 v[74:75], v[74:75], 2, s[8:9]
	v_lshl_add_u64 v[76:77], v[76:77], 2, s[8:9]
	v_lshl_add_u64 v[78:79], v[78:79], 2, s[8:9]
	v_mad_i64_i32 v[114:115], s[38:39], v82, s33, v[32:33]
	v_mad_i64_i32 v[118:119], s[38:39], v86, s33, v[32:33]
	v_mad_i64_i32 v[122:123], s[38:39], v90, s33, v[32:33]
	v_mad_i64_i32 v[126:127], s[38:39], v94, s33, v[32:33]
	global_load_dword v98, v[100:101], off
	global_load_dword v99, v[102:103], off
	s_nop 0
	global_load_dword v100, v[104:105], off
	global_load_dword v101, v[106:107], off
	global_load_dword v102, v[108:109], off
	global_load_dword v103, v[110:111], off
	s_nop 0
	global_load_dword v104, v[112:113], off
	global_load_dword v105, v[114:115], off
	v_lshl_add_u64 v[80:81], v[80:81], 2, s[8:9]
	v_lshl_add_u64 v[82:83], v[82:83], 2, s[8:9]
	global_load_dword v106, v[116:117], off
	global_load_dword v107, v[118:119], off
	v_lshl_add_u64 v[84:85], v[84:85], 2, s[8:9]
	v_lshl_add_u64 v[86:87], v[86:87], 2, s[8:9]
	global_load_dword v108, v[120:121], off
	global_load_dword v109, v[122:123], off
	v_lshl_add_u64 v[88:89], v[88:89], 2, s[8:9]
	v_lshl_add_u64 v[90:91], v[90:91], 2, s[8:9]
	global_load_dword v110, v[124:125], off
	global_load_dword v111, v[126:127], off
	v_lshl_add_u64 v[92:93], v[92:93], 2, s[8:9]
	v_lshl_add_u64 v[94:95], v[94:95], 2, s[8:9]
	global_load_dword v50, v[50:51], off
	s_nop 0
	global_load_dword v51, v[52:53], off
	s_nop 0
	global_load_dword v52, v[54:55], off
	global_load_dword v53, v[56:57], off
	s_nop 0
	global_load_dword v54, v[72:73], off
	global_load_dword v55, v[74:75], off
	global_load_dword v56, v[76:77], off
	global_load_dword v57, v[78:79], off
	s_nop 0
	global_load_dword v72, v[80:81], off
	global_load_dword v73, v[82:83], off
	global_load_dword v74, v[84:85], off
	global_load_dword v75, v[86:87], off
	global_load_dword v76, v[88:89], off
	global_load_dword v77, v[90:91], off
	global_load_dword v78, v[92:93], off
	global_load_dword v79, v[94:95], off
	s_add_i32 s11, s11, 16
	s_add_i32 s10, s10, 16
	s_add_i32 s21, s21, -16
	v_add_u32_e32 v47, s23, v2
	v_add_u32_e32 v82, s36, v1
	v_add_u32_e32 v84, s23, v18
	v_add_u32_e32 v86, s36, v3
	v_add_u32_e32 v88, s23, v20
	v_add_u32_e32 v90, s36, v9
	v_add_u32_e32 v92, s23, v22
	v_add_u32_e32 v94, s36, v19
	v_add_u32_e32 v112, s23, v24
	v_add_u32_e32 v114, s36, v21
	v_add_u32_e32 v116, s23, v26
	v_add_u32_e32 v118, s36, v23
	v_add_u32_e32 v120, s23, v28
	v_add_u32_e32 v122, s36, v25
	v_add_u32_e32 v124, s23, v30
	v_add_u32_e32 v126, s36, v27
	s_cmp_lg_u32 s21, 0
	v_mad_u64_u32 v[80:81], s[36:37], v47, s15, v[8:9]
	v_mad_u64_u32 v[82:83], s[36:37], v82, s15, v[8:9]
	v_mad_u64_u32 v[84:85], s[36:37], v84, s15, v[8:9]
	v_mad_u64_u32 v[86:87], s[36:37], v86, s15, v[8:9]
	v_mad_u64_u32 v[88:89], s[36:37], v88, s15, v[8:9]
	v_mad_u64_u32 v[90:91], s[36:37], v90, s15, v[8:9]
	v_mad_u64_u32 v[92:93], s[36:37], v92, s15, v[8:9]
	v_mad_u64_u32 v[94:95], s[36:37], v94, s15, v[8:9]
	v_mad_u64_u32 v[112:113], s[36:37], v112, s15, v[8:9]
	v_mad_u64_u32 v[114:115], s[36:37], v114, s15, v[8:9]
	v_mad_u64_u32 v[116:117], s[36:37], v116, s15, v[8:9]
	v_mad_u64_u32 v[118:119], s[36:37], v118, s15, v[8:9]
	v_mad_u64_u32 v[120:121], s[36:37], v120, s15, v[8:9]
	v_mad_u64_u32 v[122:123], s[36:37], v122, s15, v[8:9]
	v_mad_u64_u32 v[124:125], s[36:37], v124, s15, v[8:9]
	v_mad_u64_u32 v[126:127], s[36:37], v126, s15, v[8:9]
	s_lshl_b32 s23, s11, 1
	s_lshl_b32 s36, s10, 1
	v_add_u32_e32 v134, s23, v34
	v_add_u32_e32 v136, s36, v29
	v_add_u32_e32 v138, s23, v36
	v_add_u32_e32 v140, s36, v31
	v_add_u32_e32 v192, s23, v38
	v_add_u32_e32 v194, s36, v35
; #define LDS_WAIT() asm volatile("s_waitcnt lgkmcnt(0)" ::: "memory")
; template <class KS>
; __device__ __forceinline__ void p0_transpose_item(const float* W, int K, int N, bf16* WT, int kb, int nb, int prow, LAS float* scr, int lane, const KS& ks) {
;     ...
; #pragma unroll 8
;     for (int i = 0; i < 32; ++i) { const int kk = 2 * i + (lane >> 5); scr[kk * 33 + (lane & 31)] = W[(size_t)(k0 + kk) * N + n0 + (lane & 31)] * ks(k0 + kk); }
;     LDS_WAIT(); asm volatile("" ::: "memory");
; __device__ __forceinline__ void convert_items(KArgs A, unsigned char* ws, LAS unsigned char* lds, int it0, int it1, int gw, int NGW, int wave, int lane) {
;     ...
;         if (r < CI_IN) { const int kb = r / 112, nb = r % 112, pn = nb >> 3, cbk = nb & 7; const float* g1 = A->in.g1;
;             p0_transpose_item(A->in.win, DM, NIN, WIN, kb, nb, 256 * pn + 128 * (cbk & 1) + 32 * (cbk >> 1), scr, lane, [g1](int k) { return g1[k]; }); continue; } r -= CI_IN;
	v_add_u32_e32 v196, s23, v40
	v_add_u32_e32 v198, s36, v37
	v_add_u32_e32 v200, s23, v42
	v_add_u32_e32 v202, s36, v39
	v_add_u32_e32 v204, s23, v44
	v_add_u32_e32 v206, s36, v41
	v_add_u32_e32 v208, s23, v46
	v_add_u32_e32 v210, s36, v43
	v_add_u32_e32 v212, s23, v48
	v_add_u32_e32 v214, s36, v45
	v_mad_i64_i32 v[216:217], s[38:39], v134, s33, v[32:33]
	v_ashrrev_i32_e32 v137, 31, v136
	v_ashrrev_i32_e32 v135, 31, v134
	v_ashrrev_i32_e32 v141, 31, v140
	v_ashrrev_i32_e32 v139, 31, v138
	v_ashrrev_i32_e32 v195, 31, v194
	v_ashrrev_i32_e32 v193, 31, v192
	v_ashrrev_i32_e32 v199, 31, v198
	v_ashrrev_i32_e32 v197, 31, v196
	v_mad_i64_i32 v[218:219], s[38:39], v136, s33, v[32:33]
	v_mad_i64_i32 v[220:221], s[38:39], v138, s33, v[32:33]
	v_mad_i64_i32 v[222:223], s[38:39], v140, s33, v[32:33]
	v_mad_i64_i32 v[224:225], s[38:39], v192, s33, v[32:33]
	v_mad_i64_i32 v[226:227], s[38:39], v194, s33, v[32:33]
	v_mad_i64_i32 v[228:229], s[38:39], v196, s33, v[32:33]
	v_mad_i64_i32 v[232:233], s[38:39], v198, s33, v[32:33]
	v_mad_i64_i32 v[234:235], s[38:39], v200, s33, v[32:33]
	v_ashrrev_i32_e32 v203, 31, v202
	v_ashrrev_i32_e32 v201, 31, v200
	v_mad_i64_i32 v[238:239], s[38:39], v204, s33, v[32:33]
	v_ashrrev_i32_e32 v207, 31, v206
	v_ashrrev_i32_e32 v205, 31, v204
	v_mad_i64_i32 v[242:243], s[38:39], v208, s33, v[32:33]
	v_ashrrev_i32_e32 v211, 31, v210
	v_ashrrev_i32_e32 v209, 31, v208
	v_mad_i64_i32 v[246:247], s[38:39], v212, s33, v[32:33]
	v_ashrrev_i32_e32 v215, 31, v214
	v_ashrrev_i32_e32 v213, 31, v212
	global_load_dword v216, v[216:217], off
	s_nop 0
	global_load_dword v217, v[218:219], off
	v_lshl_add_u64 v[134:135], v[134:135], 2, s[8:9]
	v_lshl_add_u64 v[136:137], v[136:137], 2, s[8:9]
	v_lshl_add_u64 v[138:139], v[138:139], 2, s[8:9]
	v_lshl_add_u64 v[140:141], v[140:141], 2, s[8:9]
	v_lshl_add_u64 v[192:193], v[192:193], 2, s[8:9]
	v_lshl_add_u64 v[194:195], v[194:195], 2, s[8:9]
	v_lshl_add_u64 v[196:197], v[196:197], 2, s[8:9]
	v_lshl_add_u64 v[198:199], v[198:199], 2, s[8:9]
	v_mad_i64_i32 v[236:237], s[38:39], v202, s33, v[32:33]
	v_mad_i64_i32 v[240:241], s[38:39], v206, s33, v[32:33]
	v_mad_i64_i32 v[244:245], s[38:39], v210, s33, v[32:33]
	v_mad_i64_i32 v[248:249], s[38:39], v214, s33, v[32:33]
	global_load_dword v218, v[220:221], off
	global_load_dword v219, v[222:223], off
	s_nop 0
	global_load_dword v220, v[224:225], off
	global_load_dword v221, v[226:227], off
	global_load_dword v222, v[228:229], off
	global_load_dword v223, v[232:233], off
	s_nop 0
	global_load_dword v224, v[234:235], off
	global_load_dword v225, v[236:237], off
	v_lshl_add_u64 v[200:201], v[200:201], 2, s[8:9]
	v_lshl_add_u64 v[202:203], v[202:203], 2, s[8:9]
	global_load_dword v226, v[238:239], off
	global_load_dword v227, v[240:241], off
	v_lshl_add_u64 v[204:205], v[204:205], 2, s[8:9]
	v_lshl_add_u64 v[206:207], v[206:207], 2, s[8:9]
	global_load_dword v228, v[242:243], off
	global_load_dword v229, v[244:245], off
	v_lshl_add_u64 v[208:209], v[208:209], 2, s[8:9]
	v_lshl_add_u64 v[210:211], v[210:211], 2, s[8:9]
	global_load_dword v232, v[246:247], off
	global_load_dword v233, v[248:249], off
	v_lshl_add_u64 v[212:213], v[212:213], 2, s[8:9]
	v_lshl_add_u64 v[214:215], v[214:215], 2, s[8:9]
	global_load_dword v134, v[134:135], off
	s_nop 0
	global_load_dword v135, v[136:137], off
	s_nop 0
	global_load_dword v136, v[138:139], off
	global_load_dword v137, v[140:141], off
	s_nop 0
	global_load_dword v138, v[192:193], off
	global_load_dword v139, v[194:195], off
	global_load_dword v140, v[196:197], off
	global_load_dword v141, v[198:199], off
	s_nop 0
	global_load_dword v192, v[200:201], off
	global_load_dword v193, v[202:203], off
	global_load_dword v194, v[204:205], off
	global_load_dword v195, v[206:207], off
	global_load_dword v196, v[208:209], off
	global_load_dword v197, v[210:211], off
	global_load_dword v198, v[212:213], off
	global_load_dword v199, v[214:215], off
	s_add_i32 s11, s11, 16
	s_add_i32 s10, s10, 16
	s_add_i32 s21, s21, -16
	v_add_u32_e32 v133, s23, v2
	v_add_u32_e32 v202, s36, v1
	v_add_u32_e32 v204, s23, v18
	v_add_u32_e32 v206, s36, v3
	v_add_u32_e32 v208, s23, v20
	v_add_u32_e32 v210, s36, v9
	v_add_u32_e32 v212, s23, v22
	v_add_u32_e32 v214, s36, v19
	v_add_u32_e32 v234, s23, v24
	v_add_u32_e32 v236, s36, v21
	v_add_u32_e32 v238, s23, v26
	v_add_u32_e32 v240, s36, v23
	v_add_u32_e32 v242, s23, v28
	v_add_u32_e32 v244, s36, v25
	v_add_u32_e32 v246, s23, v30
	v_add_u32_e32 v248, s36, v27
	s_cmp_lg_u32 s21, 0
	v_mad_u64_u32 v[200:201], s[36:37], v133, s15, v[8:9]
	v_mad_u64_u32 v[202:203], s[36:37], v202, s15, v[8:9]
	v_mad_u64_u32 v[204:205], s[36:37], v204, s15, v[8:9]
	v_mad_u64_u32 v[206:207], s[36:37], v206, s15, v[8:9]
	v_mad_u64_u32 v[208:209], s[36:37], v208, s15, v[8:9]
	v_mad_u64_u32 v[210:211], s[36:37], v210, s15, v[8:9]
	v_mad_u64_u32 v[212:213], s[36:37], v212, s15, v[8:9]
	v_mad_u64_u32 v[214:215], s[36:37], v214, s15, v[8:9]
	v_mad_u64_u32 v[234:235], s[36:37], v234, s15, v[8:9]
	v_mad_u64_u32 v[236:237], s[36:37], v236, s15, v[8:9]
	v_mad_u64_u32 v[238:239], s[36:37], v238, s15, v[8:9]
	v_mad_u64_u32 v[240:241], s[36:37], v240, s15, v[8:9]
	v_mad_u64_u32 v[242:243], s[36:37], v242, s15, v[8:9]
	v_mad_u64_u32 v[244:245], s[36:37], v244, s15, v[8:9]
	v_mad_u64_u32 v[246:247], s[36:37], v246, s15, v[8:9]
	v_mad_u64_u32 v[248:249], s[36:37], v248, s15, v[8:9]
	s_waitcnt vmcnt(46)
; #define GAS __attribute__((address_space(1)))
; #define LAS __attribute__((address_space(3)))
; #define LDS_WAIT() asm volatile("s_waitcnt lgkmcnt(0)" ::: "memory")
; __device__ __forceinline__ unsigned pk2(float lo, float hi) { return pg8::cvt_pk_bf16(lo, hi); }
; template <class KS>
; __device__ __forceinline__ void p0_transpose_item(const float* W, int K, int N, bf16* WT, int kb, int nb, int prow, LAS float* scr, int lane, const KS& ks) {
;     ...
;     for (int i = 0; i < 32; ++i) { const int kk = 2 * i + (lane >> 5); scr[kk * 33 + (lane & 31)] = W[(size_t)(k0 + kk) * N + n0 + (lane & 31)] * ks(k0 + kk); }
;     LDS_WAIT(); asm volatile("" ::: "memory");
;     const int c = lane & 7;
; #pragma unroll
;     for (int j = 0; j < 4; ++j) { const int n = (lane >> 3) + 8 * j; const LAS float* s = scr + (8 * c) * 33 + n;
;         v4u o; o.x = pk2(s[0 * 33], s[1 * 33]); o.y = pk2(s[2 * 33], s[3 * 33]); o.z = pk2(s[4 * 33], s[5 * 33]); o.w = pk2(s[6 * 33], s[7 * 33]);
;         *(GAS v4u*)(WT + (size_t)(prow + n) * K + k0 + 8 * c) = o; }
;     LDS_WAIT(); asm volatile("" ::: "memory");
	v_pk_mul_f32 v[50:51], v[96:97], v[50:51]
	s_waitcnt vmcnt(44)
	v_pk_mul_f32 v[52:53], v[98:99], v[52:53]
	s_waitcnt vmcnt(42)
	v_pk_mul_f32 v[54:55], v[100:101], v[54:55]
	s_waitcnt vmcnt(40)
	v_pk_mul_f32 v[56:57], v[102:103], v[56:57]
	s_waitcnt vmcnt(38)
	v_pk_mul_f32 v[72:73], v[104:105], v[72:73]
	s_waitcnt vmcnt(36)
	v_pk_mul_f32 v[74:75], v[106:107], v[74:75]
	s_waitcnt vmcnt(34)
	v_pk_mul_f32 v[76:77], v[108:109], v[76:77]
	s_waitcnt vmcnt(32)
	v_pk_mul_f32 v[78:79], v[110:111], v[78:79]
	ds_write_b32 v80, v50
	ds_write_b32 v82, v51
	ds_write_b32 v84, v52
	ds_write_b32 v86, v53
	ds_write_b32 v88, v54
	ds_write_b32 v90, v55
	ds_write_b32 v92, v56
	ds_write_b32 v94, v57
	ds_write_b32 v112, v72
	ds_write_b32 v114, v73
	ds_write_b32 v116, v74
	ds_write_b32 v118, v75
	ds_write_b32 v120, v76
	ds_write_b32 v122, v77
	ds_write_b32 v124, v78
	ds_write_b32 v126, v79
	s_waitcnt vmcnt(14)
	v_pk_mul_f32 v[134:135], v[216:217], v[134:135]
	s_waitcnt vmcnt(12)
	v_pk_mul_f32 v[136:137], v[218:219], v[136:137]
	s_waitcnt vmcnt(10)
	v_pk_mul_f32 v[138:139], v[220:221], v[138:139]
	s_waitcnt vmcnt(8)
	v_pk_mul_f32 v[140:141], v[222:223], v[140:141]
	s_waitcnt vmcnt(6)
	v_pk_mul_f32 v[192:193], v[224:225], v[192:193]
	s_waitcnt vmcnt(4)
	v_pk_mul_f32 v[194:195], v[226:227], v[194:195]
	s_waitcnt vmcnt(2)
	v_pk_mul_f32 v[196:197], v[228:229], v[196:197]
	s_waitcnt vmcnt(0)
	v_pk_mul_f32 v[198:199], v[232:233], v[198:199]
	ds_write_b32 v200, v134
	ds_write_b32 v202, v135
	ds_write_b32 v204, v136
	ds_write_b32 v206, v137
	ds_write_b32 v208, v138
	ds_write_b32 v210, v139
	ds_write_b32 v212, v140
	ds_write_b32 v214, v141
	ds_write_b32 v234, v192
	ds_write_b32 v236, v193
	ds_write_b32 v238, v194
	ds_write_b32 v240, v195
	ds_write_b32 v242, v196
	ds_write_b32 v244, v197
	ds_write_b32 v246, v198
	ds_write_b32 v248, v199
	s_lshl_b32 s8, s6, 7
	s_waitcnt lgkmcnt(0)
	s_lshl_b32 s6, s6, 4
	s_and_b32 s8, s8, 0x80
	s_and_b32 s9, s22, 0xffffff00
	s_and_b32 s6, s6, 0x60
	s_or_b32 s8, s9, s8
	ds_read2_b32 v[36:37], v58 offset0:33 offset1:41
	ds_read2_b32 v[38:39], v58 offset1:8
	ds_read2_b32 v[40:41], v58 offset0:66 offset1:74
	ds_read2_b32 v[42:43], v58 offset0:99 offset1:107
	ds_read2_b32 v[44:45], v58 offset0:132 offset1:140
	ds_read2_b32 v[46:47], v58 offset0:165 offset1:173
	ds_read2_b32 v[50:51], v58 offset0:198 offset1:206
	ds_read2_b32 v[52:53], v58 offset0:231 offset1:239
	s_or_b32 s6, s8, s6
	v_add_u32_e32 v56, s6, v49
	s_ashr_i32 s21, s20, 31
	v_ashrrev_i32_e32 v57, 31, v56
	v_lshl_add_u64 v[54:55], s[20:21], 1, v[16:17]
	v_lshlrev_b64 v[56:57], 11, v[56:57]
	s_waitcnt lgkmcnt(6)
	v_cvt_pk_bf16_f32 v32, v38, v36
	s_waitcnt lgkmcnt(4)
	v_cvt_pk_bf16_f32 v33, v40, v42
	s_waitcnt lgkmcnt(2)
	v_cvt_pk_bf16_f32 v34, v44, v46
	s_waitcnt lgkmcnt(0)
	v_cvt_pk_bf16_f32 v35, v50, v52
	v_lshl_add_u64 v[56:57], v[54:55], 0, v[56:57]
	v_add_u32_e32 v36, s6, v59
	global_store_dwordx4 v[56:57], v[32:35], off
	s_nop 1
	v_cvt_pk_bf16_f32 v32, v39, v37
	v_ashrrev_i32_e32 v37, 31, v36
	v_cvt_pk_bf16_f32 v33, v41, v43
	v_cvt_pk_bf16_f32 v34, v45, v47
	v_cvt_pk_bf16_f32 v35, v51, v53
	v_lshlrev_b64 v[36:37], 11, v[36:37]
	ds_read2_b32 v[38:39], v58 offset0:49 offset1:57
	ds_read2_b32 v[40:41], v58 offset0:16 offset1:24
	ds_read2_b32 v[42:43], v58 offset0:82 offset1:90
	ds_read2_b32 v[44:45], v58 offset0:115 offset1:123
	ds_read2_b32 v[46:47], v58 offset0:148 offset1:156
	ds_read2_b32 v[50:51], v58 offset0:181 offset1:189
	ds_read2_b32 v[52:53], v58 offset0:214 offset1:222
	ds_read2_b32 v[56:57], v58 offset0:247 offset1:255
	v_lshl_add_u64 v[36:37], v[54:55], 0, v[36:37]
	global_store_dwordx4 v[36:37], v[32:35], off
	v_add_u32_e32 v36, s6, v60
	v_ashrrev_i32_e32 v37, 31, v36
	v_lshlrev_b64 v[36:37], 11, v[36:37]
	s_waitcnt lgkmcnt(6)
	v_cvt_pk_bf16_f32 v32, v40, v38
	s_waitcnt lgkmcnt(4)
	v_cvt_pk_bf16_f32 v33, v42, v44
	s_waitcnt lgkmcnt(2)
	v_cvt_pk_bf16_f32 v34, v46, v50
	s_waitcnt lgkmcnt(0)
	v_cvt_pk_bf16_f32 v35, v52, v56
	v_lshl_add_u64 v[36:37], v[54:55], 0, v[36:37]
	global_store_dwordx4 v[36:37], v[32:35], off
	v_add_u32_e32 v36, s6, v61
	v_ashrrev_i32_e32 v37, 31, v36
	v_lshlrev_b64 v[36:37], 11, v[36:37]
	v_cvt_pk_bf16_f32 v32, v41, v39
	v_cvt_pk_bf16_f32 v33, v43, v45
	v_cvt_pk_bf16_f32 v34, v47, v51
	v_cvt_pk_bf16_f32 v35, v53, v57
	v_lshl_add_u64 v[36:37], v[54:55], 0, v[36:37]
	global_store_dwordx4 v[36:37], v[32:35], off
	s_waitcnt lgkmcnt(0)
	s_branch .LBB0_20
